# SSD: static s_setprio 1 for the wave of each SIMD pair that owns more causal blocks (waves 4-7 forward, 0-3 backward)
# speedup vs baseline: 1.0133x; 1.0133x over previous
.LBB0_1072:
	s_ashr_i32 s0, s80, 31
	s_lshr_b32 s1, s0, 29
	s_lshr_b32 s0, s0, 30
	s_add_i32 s0, s80, s0
	s_bfe_u32 s14, s0, 0x10002
	s_lshr_b32 s0, s80, 31
	s_add_i32 s0, s80, s0
	s_bfe_u32 s3, s0, 0x10001
	s_and_b32 s0, s0, 0x3ffffffe
	s_add_i32 s1, s80, s1
	s_sub_i32 s0, s80, s0
	s_ashr_i32 s2, s1, 3
	v_readfirstlane_b32 s1, v182
	s_lshl_b32 s4, s14, 3
	s_lshl_b32 s0, s0, 2
	s_add_i32 s0, s4, s0
	s_bfe_u32 s15, s1, 0x20006
	s_cmp_eq_u32 s3, 0
	s_cselect_b64 s[4:5], -1, 0
	s_setprio 0
	s_bfe_u32 s88, s1, 0x10008
	s_cmp_lg_u32 s88, s3
	s_cbranch_scc0 .Lssd_prio_lo
	s_setprio 1
.Lssd_prio_lo:
	s_and_b64 vcc, s[4:5], exec
	v_readlane_b32 s6, v254, 9
	v_readlane_b32 s7, v254, 11
	s_cselect_b32 s16, s6, s7
	v_readlane_b32 s6, v254, 8
	v_readlane_b32 s7, v254, 10
	s_cselect_b32 s17, s6, s7
	s_or_b32 s6, s15, s0
	s_ashr_i32 s7, s6, 31
	s_lshl_b64 s[6:7], s[6:7], 2
	s_add_u32 s6, s17, s6
	s_addc_u32 s7, s16, s7
	v_mov_b64_e32 v[2:3], s[6:7]
	flat_load_dword v0, v[2:3]
	s_mov_b64 s[6:7], -1
	s_cbranch_vccnz .LBB0_1074
	s_lshl_b32 s18, s2, 22
	s_add_i32 s16, s18, 0x4000000
	s_mov_b64 s[6:7], 0

.LBB0_1144:
	s_setprio 0
	s_cmp_gt_i32 s87, 7
	v_readlane_b32 s2, v254, 6
	s_cselect_b64 s[0:1], -1, 0
	v_readlane_b32 s3, v254, 7
	s_and_b64 s[2:3], s[2:3], s[0:1]
	s_andn2_b64 vcc, exec, s[2:3]
	s_cbranch_vccnz .LBB0_1198
	s_getreg_b32 s4, hwreg(HW_REG_XCC_ID, 0, 4)
	s_waitcnt vmcnt(0)
	s_waitcnt vmcnt(0) lgkmcnt(0)
	s_barrier
	s_mov_b64 s[2:3], exec
	v_readlane_b32 s6, v254, 4
	v_readlane_b32 s7, v254, 5
	s_and_b64 s[6:7], s[2:3], s[6:7]
	s_mov_b64 exec, s[6:7]
	s_cbranch_execz .LBB0_1197
	s_add_i32 s5, 0, 0x27f00
	v_mov_b32_e32 v0, s5
	s_waitcnt vmcnt(0) expcnt(0) lgkmcnt(0)
	ds_read_b32 v2, v0
	s_add_i32 s5, 0, 0x27f04
	v_mov_b32_e32 v0, s5
	ds_read_b32 v0, v0
	s_and_b32 s33, s4, 15
	s_waitcnt lgkmcnt(1)
	v_cmp_ne_u32_e32 vcc, 0, v2
	s_cbranch_vccnz .LBB0_1161
	v_readlane_b32 s4, v254, 2
	v_readlane_b32 s5, v254, 3
	s_load_dwordx2 s[8:9], s[4:5], 0x4
	s_add_u32 s4, s84, 0x80200
	s_addc_u32 s5, s85, 0
	s_add_u32 s6, s84, 0x80400
	s_addc_u32 s7, s85, 0
	s_waitcnt lgkmcnt(0)
	s_mul_i32 s46, s8, s82
	s_add_u32 s8, s84, 0x80500
	s_mul_i32 s46, s46, s9
	s_addc_u32 s9, s85, 0
	s_add_u32 s10, s84, 0x80600
	s_addc_u32 s11, s85, 0
	s_add_u32 s12, s84, 0x80700
	s_addc_u32 s13, s85, 0
	s_add_u32 s14, s84, 0x80800
	s_addc_u32 s15, s85, 0
	s_add_u32 s16, s84, 0x80900
	s_addc_u32 s17, s85, 0
	s_add_u32 s18, s84, 0x80a00
	s_addc_u32 s19, s85, 0
	s_add_u32 s20, s84, 0x80b00
	s_addc_u32 s21, s85, 0
	s_add_u32 s22, s84, 0x80c00
	s_addc_u32 s23, s85, 0
	s_add_u32 s24, s84, 0x80d00
	s_addc_u32 s25, s85, 0
	s_add_u32 s26, s84, 0x80e00
	s_addc_u32 s27, s85, 0
	s_add_u32 s28, s84, 0x80f00
	s_addc_u32 s29, s85, 0
	s_add_u32 s30, s84, 0x81000
	s_addc_u32 s31, s85, 0
	s_add_u32 s34, s84, 0x81100
	s_addc_u32 s35, s85, 0
	s_add_u32 s36, s84, 0x81200
	s_addc_u32 s37, s85, 0
	s_add_u32 s38, s84, 0x81300
	s_addc_u32 s39, s85, 0
	s_mov_b32 s47, 1
	v_mov_b32_e32 v16, 0
	s_branch .LBB0_1149
